# P2 in-proj GEMM loop: per-phase s_setprio flips deleted, one static s_setprio 1 for waves 0-3 (the leading wave group) for the whole phase
# speedup vs baseline: 1.0104x; 1.0001x over previous
; #define PG8_STAGE(bufoff, gbase, voff) do { _Pragma("unroll") for (int _i = 0; _i < 2; ++_i) \
;         __builtin_amdgcn_global_load_lds((const unsigned*)((const char*)(gbase) + (voff)[_i]), (LAS unsigned*)(lds + (bufoff) + ldsw + _i * 8192), 16, 0, 0); } while (0)
; #define PG8_WAIT_V(n) asm volatile("s_waitcnt vmcnt(" #n ")" ::: "memory")
; #define PG8_BAR __builtin_amdgcn_s_barrier()
; template <class Epi, class Sched>
; __device__ __forceinline__ void gemm_phase(LAS unsigned char* lds, const Gemm g, const Sched& S, const Epi& E) {
;     ...
;     if (wr == 1) PG8_BAR;
;     PG8_WAIT_V(4); PG8_BAR;
;     PG8_STAGE(PG8_SB(1, 0), cB + kstep, voffB); PG8_STAGE(PG8_SA(1, 0), cA + kstep, voffA); PG8_STAGE(PG8_SB(1, 1), cB + hstepB + kstep, voffB);
;     PG8_WAIT_V(6); PG8_BAR;
.LBB0_135:
	s_cmp_lg_u32 s1, 0
	s_cbranch_scc1 .Lp2prio
	s_setprio 1

; #define PG8_STAGE(bufoff, gbase, voff) do { _Pragma("unroll") for (int _i = 0; _i < 2; ++_i) \
;         __builtin_amdgcn_global_load_lds((const unsigned*)((const char*)(gbase) + (voff)[_i]), (LAS unsigned*)(lds + (bufoff) + ldsw + _i * 8192), 16, 0, 0); } while (0)
; #define PG8_LDA(dst, b, h) do { _Pragma("unroll") for (int m = 0; m < 4; ++m) _Pragma("unroll") for (int k = 0; k < 2; ++k) dst[m][k] = *(const LAS bf16x8*)(lds + PG8_SA(b, h) + aoff + m * 2048 + k * 1024); } while (0)
; #define PG8_LDB(dst, b, h) do { _Pragma("unroll") for (int n = 0; n < 2; ++n) _Pragma("unroll") for (int k = 0; k < 2; ++k) dst[n][k] = *(const LAS bf16x8*)(lds + PG8_SB(b, h) + boff + n * 2048 + k * 1024); } while (0)
; #define PG8_MMA(ai, bj, At, Bt) do { __builtin_amdgcn_s_setprio(1); _Pragma("unroll") for (int m = 0; m < 4; ++m) _Pragma("unroll") for (int n = 0; n < 2; ++n) _Pragma("unroll") for (int k = 0; k < 2; ++k) \
;         acc[ai][bj][m][n] = __builtin_amdgcn_mfma_f32_16x16x32_bf16(Bt[n][k], At[m][k], acc[ai][bj][m][n], 0, 0, 0); __builtin_amdgcn_s_setprio(0); } while (0)
; #define PG8_WAIT_L(n) asm volatile("s_waitcnt lgkmcnt(" #n ")" ::: "memory")
; #define PG8_BAR __builtin_amdgcn_s_barrier()
; #define PG8_SCHED __builtin_amdgcn_sched_barrier(0)
; template <class Epi, class Sched>
; __device__ __forceinline__ void gemm_phase(LAS unsigned char* lds, const Gemm g, const Sched& S, const Epi& E) {
;     ...
;             PG8_LDB(B0, 0, 0); PG8_SCHED; PG8_LDA(At, 0, 0); PG8_STAGE(PG8_SA(1, 1), a1 + hstepA, voffA);
;             PG8_WAIT_L(8); PG8_BAR; PG8_WAIT_L(0); PG8_MMA(0, 0, At, B0); PG8_BAR; PG8_SCHED;
;             PG8_LDB(B1, 0, 1); PG8_STAGE(PG8_SB(0, 0), b2, voffB);
;             PG8_BAR; PG8_WAIT_L(0); PG8_MMA(0, 1, At, B1); PG8_BAR;
;             PG8_LDA(At, 0, 1); PG8_STAGE(PG8_SA(0, 0), a2, voffA);
;             PG8_BAR; PG8_WAIT_L(0); PG8_MMA(1, 0, At, B0); PG8_BAR; PG8_SCHED;
.LBB0_140:
	s_add_u32 s49, s70, 0xfffc0080
	s_addc_u32 s51, s71, -1
	s_add_i32 vcc_lo, 0, 0x10000
	v_add_u32_e32 v129, vcc_lo, v164
	ds_read_b128 v[150:153], v129
	ds_read_b128 v[154:157], v129 offset:1024
	ds_read_b128 v[168:171], v129 offset:2048
	ds_read_b128 v[172:175], v129 offset:3072
	s_cmp_eq_u32 s29, 12
	s_cselect_b32 s75, s11, s51
	s_cselect_b32 s74, s14, s49
	s_cselect_b32 s73, s25, s28
	s_cselect_b32 s72, s26, s27
	v_lshl_add_u64 v[158:159], s[70:71], 0, v[144:145]
	s_add_i32 m0, s96, 0xc000
	ds_read_b128 v[176:179], v165
	ds_read_b128 v[180:183], v165 offset:1024
	ds_read_b128 v[184:187], v165 offset:2048
	ds_read_b128 v[188:191], v165 offset:3072
	ds_read_b128 v[192:195], v165 offset:4096
	ds_read_b128 v[196:199], v165 offset:5120
	ds_read_b128 v[200:203], v165 offset:6144
	ds_read_b128 v[204:207], v165 offset:7168
	global_load_lds_dwordx4 v[158:159], off
	v_lshl_add_u64 v[158:159], s[70:71], 0, v[146:147]
	s_add_i32 m0, s96, 0xe000
	s_nop 0
	global_load_lds_dwordx4 v[158:159], off
	s_waitcnt lgkmcnt(8)
	s_barrier
	s_waitcnt lgkmcnt(0)
	s_waitcnt lgkmcnt(0)
	v_mfma_f32_16x16x32_bf16 v[124:127], v[150:153], v[176:179], v[124:127]
	v_mfma_f32_16x16x32_bf16 v[120:123], v[168:171], v[176:179], v[120:123]
	v_mfma_f32_16x16x32_bf16 v[112:115], v[150:153], v[184:187], v[112:115]
	v_mfma_f32_16x16x32_bf16 v[104:107], v[168:171], v[184:187], v[104:107]
	v_mfma_f32_16x16x32_bf16 v[96:99], v[150:153], v[192:195], v[96:99]
	v_mfma_f32_16x16x32_bf16 v[88:91], v[168:171], v[192:195], v[88:91]
	v_mfma_f32_16x16x32_bf16 v[80:83], v[150:153], v[200:203], v[80:83]
	v_mfma_f32_16x16x32_bf16 v[72:75], v[168:171], v[200:203], v[72:75]
	v_mfma_f32_16x16x32_bf16 v[124:127], v[154:157], v[180:183], v[124:127]
	v_mfma_f32_16x16x32_bf16 v[120:123], v[172:175], v[180:183], v[120:123]
	v_mfma_f32_16x16x32_bf16 v[112:115], v[154:157], v[188:191], v[112:115]
	v_mfma_f32_16x16x32_bf16 v[104:107], v[172:175], v[188:191], v[104:107]
	v_mfma_f32_16x16x32_bf16 v[96:99], v[154:157], v[196:199], v[96:99]
	v_mfma_f32_16x16x32_bf16 v[88:91], v[172:175], v[196:199], v[88:91]
	v_mfma_f32_16x16x32_bf16 v[80:83], v[154:157], v[204:207], v[80:83]
	v_mfma_f32_16x16x32_bf16 v[72:75], v[172:175], v[204:207], v[72:75]
	s_barrier
	s_add_i32 s49, 0, 0x14000
	s_add_i32 s51, vcc_lo, s95
	v_add_u32_e32 v129, s49, v164
	v_lshl_add_u64 v[158:159], s[72:73], 0, v[138:139]
	s_mov_b32 m0, s51
	ds_read_b128 v[208:211], v129
	ds_read_b128 v[212:215], v129 offset:1024
	ds_read_b128 v[216:219], v129 offset:2048
	ds_read_b128 v[220:223], v129 offset:3072
	global_load_lds_dwordx4 v[158:159], off
	v_lshl_add_u64 v[224:225], s[72:73], 0, v[134:135]
	s_add_i32 m0, s51, 0x2000
	s_nop 0
	global_load_lds_dwordx4 v[224:225], off
	s_barrier
	s_waitcnt lgkmcnt(0)
	s_waitcnt lgkmcnt(0)
	v_mfma_f32_16x16x32_bf16 v[116:119], v[208:211], v[176:179], v[116:119]
	v_mfma_f32_16x16x32_bf16 v[108:111], v[216:219], v[176:179], v[108:111]
	v_mfma_f32_16x16x32_bf16 v[100:103], v[208:211], v[184:187], v[100:103]
	v_mfma_f32_16x16x32_bf16 v[92:95], v[216:219], v[184:187], v[92:95]
	v_mfma_f32_16x16x32_bf16 v[84:87], v[208:211], v[192:195], v[84:87]
	v_mfma_f32_16x16x32_bf16 v[76:79], v[216:219], v[192:195], v[76:79]
	v_mfma_f32_16x16x32_bf16 v[68:71], v[208:211], v[200:203], v[68:71]
	v_mfma_f32_16x16x32_bf16 v[64:67], v[216:219], v[200:203], v[64:67]
	v_mfma_f32_16x16x32_bf16 v[116:119], v[212:215], v[180:183], v[116:119]
	v_mfma_f32_16x16x32_bf16 v[108:111], v[220:223], v[180:183], v[108:111]
	v_mfma_f32_16x16x32_bf16 v[100:103], v[212:215], v[188:191], v[100:103]
	v_mfma_f32_16x16x32_bf16 v[92:95], v[220:223], v[188:191], v[92:95]
	v_mfma_f32_16x16x32_bf16 v[84:87], v[212:215], v[196:199], v[84:87]
	v_mfma_f32_16x16x32_bf16 v[76:79], v[220:223], v[196:199], v[76:79]
	v_mfma_f32_16x16x32_bf16 v[68:71], v[212:215], v[204:207], v[68:71]
	v_mfma_f32_16x16x32_bf16 v[64:67], v[220:223], v[204:207], v[64:67]
	s_mov_b32 m0, s96
	v_lshl_add_u64 v[226:227], s[74:75], 0, v[140:141]
	s_barrier
	ds_read_b128 v[176:179], v165 offset:16384
	ds_read_b128 v[180:183], v165 offset:17408
	ds_read_b128 v[184:187], v165 offset:18432
	ds_read_b128 v[188:191], v165 offset:19456
	ds_read_b128 v[192:195], v165 offset:20480
	ds_read_b128 v[196:199], v165 offset:21504
	ds_read_b128 v[200:203], v165 offset:22528
	ds_read_b128 v[204:207], v165 offset:23552
	global_load_lds_dwordx4 v[226:227], off
	v_lshl_add_u64 v[228:229], s[74:75], 0, v[136:137]
	s_mov_b32 m0, s97
	s_nop 0
	global_load_lds_dwordx4 v[228:229], off
	s_barrier
	s_waitcnt lgkmcnt(0)
	s_waitcnt lgkmcnt(0)
	v_mfma_f32_16x16x32_bf16 v[60:63], v[150:153], v[176:179], v[60:63]
	v_mfma_f32_16x16x32_bf16 v[56:59], v[168:171], v[176:179], v[56:59]
	v_mfma_f32_16x16x32_bf16 v[48:51], v[150:153], v[184:187], v[48:51]
	v_mfma_f32_16x16x32_bf16 v[40:43], v[168:171], v[184:187], v[40:43]
	v_mfma_f32_16x16x32_bf16 v[36:39], v[150:153], v[192:195], v[36:39]
	v_mfma_f32_16x16x32_bf16 v[28:31], v[168:171], v[192:195], v[28:31]
	v_mfma_f32_16x16x32_bf16 v[20:23], v[150:153], v[200:203], v[20:23]
	v_mfma_f32_16x16x32_bf16 v[12:15], v[168:171], v[200:203], v[12:15]
	v_mfma_f32_16x16x32_bf16 v[60:63], v[154:157], v[180:183], v[60:63]
	v_mfma_f32_16x16x32_bf16 v[56:59], v[172:175], v[180:183], v[56:59]
	v_mfma_f32_16x16x32_bf16 v[48:51], v[154:157], v[188:191], v[48:51]
	v_mfma_f32_16x16x32_bf16 v[40:43], v[172:175], v[188:191], v[40:43]
	v_mfma_f32_16x16x32_bf16 v[36:39], v[154:157], v[196:199], v[36:39]
	v_mfma_f32_16x16x32_bf16 v[28:31], v[172:175], v[196:199], v[28:31]
	v_mfma_f32_16x16x32_bf16 v[20:23], v[154:157], v[204:207], v[20:23]
	v_mfma_f32_16x16x32_bf16 v[12:15], v[172:175], v[204:207], v[12:15]
	s_barrier
; #define PG8_STAGE(bufoff, gbase, voff) do { _Pragma("unroll") for (int _i = 0; _i < 2; ++_i) \
;         __builtin_amdgcn_global_load_lds((const unsigned*)((const char*)(gbase) + (voff)[_i]), (LAS unsigned*)(lds + (bufoff) + ldsw + _i * 8192), 16, 0, 0); } while (0)
; #define PG8_LDA(dst, b, h) do { _Pragma("unroll") for (int m = 0; m < 4; ++m) _Pragma("unroll") for (int k = 0; k < 2; ++k) dst[m][k] = *(const LAS bf16x8*)(lds + PG8_SA(b, h) + aoff + m * 2048 + k * 1024); } while (0)
; #define PG8_LDB(dst, b, h) do { _Pragma("unroll") for (int n = 0; n < 2; ++n) _Pragma("unroll") for (int k = 0; k < 2; ++k) dst[n][k] = *(const LAS bf16x8*)(lds + PG8_SB(b, h) + boff + n * 2048 + k * 1024); } while (0)
; #define PG8_MMA(ai, bj, At, Bt) do { __builtin_amdgcn_s_setprio(1); _Pragma("unroll") for (int m = 0; m < 4; ++m) _Pragma("unroll") for (int n = 0; n < 2; ++n) _Pragma("unroll") for (int k = 0; k < 2; ++k) \
;         acc[ai][bj][m][n] = __builtin_amdgcn_mfma_f32_16x16x32_bf16(Bt[n][k], At[m][k], acc[ai][bj][m][n], 0, 0, 0); __builtin_amdgcn_s_setprio(0); } while (0)
; #define PG8_WAIT_V(n) asm volatile("s_waitcnt vmcnt(" #n ")" ::: "memory")
; #define PG8_WAIT_L(n) asm volatile("s_waitcnt lgkmcnt(" #n ")" ::: "memory")
; #define PG8_BAR __builtin_amdgcn_s_barrier()
; #define PG8_SCHED __builtin_amdgcn_sched_barrier(0)
; template <class Epi, class Sched>
; __device__ __forceinline__ void gemm_phase(LAS unsigned char* lds, const Gemm g, const Sched& S, const Epi& E) {
;     ...
;             PG8_STAGE(PG8_SB(0, 1), b2 + hstepB, voffB);
;             PG8_WAIT_V(6); PG8_BAR; PG8_MMA(1, 1, At, B1); PG8_BAR;
;             PG8_LDB(B0, 1, 0); PG8_SCHED; PG8_LDA(At, 1, 0); PG8_STAGE(PG8_SA(0, 1), a2 + hstepA, voffA);
;             PG8_WAIT_L(8); PG8_BAR; PG8_WAIT_L(0); PG8_MMA(0, 0, At, B0); PG8_BAR; PG8_SCHED;
;             PG8_LDB(B1, 1, 1); PG8_STAGE(PG8_SB(1, 0), b3, voffB);
;             PG8_BAR; PG8_WAIT_L(0); PG8_MMA(0, 1, At, B1); PG8_BAR;
	s_add_u32 vcc_lo, s72, 0x40000
	s_addc_u32 vcc_hi, s73, 0
	s_add_i32 s49, s49, s95
	v_lshl_add_u64 v[150:151], vcc, 0, v[138:139]
	s_mov_b32 m0, s49
	s_nop 0
	global_load_lds_dwordx4 v[150:151], off
	v_lshl_add_u64 v[150:151], vcc, 0, v[134:135]
	s_add_i32 m0, s49, 0x2000
	s_nop 0
	global_load_lds_dwordx4 v[150:151], off
	s_waitcnt vmcnt(6)
	s_barrier
	v_mfma_f32_16x16x32_bf16 v[52:55], v[208:211], v[176:179], v[52:55]
	v_mfma_f32_16x16x32_bf16 v[44:47], v[216:219], v[176:179], v[44:47]
	v_mfma_f32_16x16x32_bf16 v[32:35], v[208:211], v[184:187], v[32:35]
	v_mfma_f32_16x16x32_bf16 v[24:27], v[216:219], v[184:187], v[24:27]
	v_mfma_f32_16x16x32_bf16 v[16:19], v[208:211], v[192:195], v[16:19]
	v_mfma_f32_16x16x32_bf16 v[8:11], v[216:219], v[192:195], v[8:11]
	v_mfma_f32_16x16x32_bf16 v[4:7], v[208:211], v[200:203], v[4:7]
	v_mfma_f32_16x16x32_bf16 v[0:3], v[216:219], v[200:203], v[0:3]
	v_mfma_f32_16x16x32_bf16 v[52:55], v[212:215], v[180:183], v[52:55]
	v_mfma_f32_16x16x32_bf16 v[44:47], v[220:223], v[180:183], v[44:47]
	v_mfma_f32_16x16x32_bf16 v[32:35], v[212:215], v[188:191], v[32:35]
	v_mfma_f32_16x16x32_bf16 v[24:27], v[220:223], v[188:191], v[24:27]
	v_mfma_f32_16x16x32_bf16 v[16:19], v[212:215], v[196:199], v[16:19]
	v_mfma_f32_16x16x32_bf16 v[8:11], v[220:223], v[196:199], v[8:11]
	v_mfma_f32_16x16x32_bf16 v[4:7], v[212:215], v[204:207], v[4:7]
	v_mfma_f32_16x16x32_bf16 v[0:3], v[220:223], v[204:207], v[0:3]
	s_add_i32 s49, 0, 0x18000
	v_add_u32_e32 v129, s49, v164
	s_barrier
	ds_read_b128 v[150:153], v129
	ds_read_b128 v[154:157], v129 offset:1024
	ds_read_b128 v[168:171], v129 offset:2048
	ds_read_b128 v[172:175], v129 offset:3072
	s_add_u32 s74, s74, 0x40000
	s_addc_u32 s75, s75, 0
	s_mov_b32 m0, s33
	v_lshl_add_u64 v[208:209], s[74:75], 0, v[140:141]
	ds_read_b128 v[176:179], v165 offset:32768
	ds_read_b128 v[180:183], v165 offset:33792
	ds_read_b128 v[184:187], v165 offset:34816
	ds_read_b128 v[188:191], v165 offset:35840
	ds_read_b128 v[192:195], v165 offset:36864
	ds_read_b128 v[196:199], v165 offset:37888
	ds_read_b128 v[200:203], v165 offset:38912
	ds_read_b128 v[204:207], v165 offset:39936
	global_load_lds_dwordx4 v[208:209], off
	v_lshl_add_u64 v[208:209], s[74:75], 0, v[136:137]
	s_mov_b32 m0, s6
	s_nop 0
	global_load_lds_dwordx4 v[208:209], off
	s_waitcnt lgkmcnt(8)
	s_barrier
	s_waitcnt lgkmcnt(0)
	s_waitcnt lgkmcnt(0)
	v_mfma_f32_16x16x32_bf16 v[124:127], v[150:153], v[176:179], v[124:127]
	v_mfma_f32_16x16x32_bf16 v[120:123], v[168:171], v[176:179], v[120:123]
	v_mfma_f32_16x16x32_bf16 v[112:115], v[150:153], v[184:187], v[112:115]
	v_mfma_f32_16x16x32_bf16 v[104:107], v[168:171], v[184:187], v[104:107]
	v_mfma_f32_16x16x32_bf16 v[96:99], v[150:153], v[192:195], v[96:99]
	v_mfma_f32_16x16x32_bf16 v[88:91], v[168:171], v[192:195], v[88:91]
	v_mfma_f32_16x16x32_bf16 v[80:83], v[150:153], v[200:203], v[80:83]
	v_mfma_f32_16x16x32_bf16 v[72:75], v[168:171], v[200:203], v[72:75]
	v_mfma_f32_16x16x32_bf16 v[124:127], v[154:157], v[180:183], v[124:127]
	v_mfma_f32_16x16x32_bf16 v[120:123], v[172:175], v[180:183], v[120:123]
	v_mfma_f32_16x16x32_bf16 v[112:115], v[154:157], v[188:191], v[112:115]
	v_mfma_f32_16x16x32_bf16 v[104:107], v[172:175], v[188:191], v[104:107]
	v_mfma_f32_16x16x32_bf16 v[96:99], v[154:157], v[196:199], v[96:99]
	v_mfma_f32_16x16x32_bf16 v[88:91], v[172:175], v[196:199], v[88:91]
	v_mfma_f32_16x16x32_bf16 v[80:83], v[154:157], v[204:207], v[80:83]
	v_mfma_f32_16x16x32_bf16 v[72:75], v[172:175], v[204:207], v[72:75]
	s_barrier
	s_add_i32 s51, 0, 0x1c000
	s_add_i32 s49, s49, s95
	v_add_u32_e32 v129, s51, v164
	v_lshl_add_u64 v[158:159], v[158:159], 0, s[46:47]
	s_mov_b32 m0, s49
	ds_read_b128 v[208:211], v129
	ds_read_b128 v[212:215], v129 offset:1024
	ds_read_b128 v[216:219], v129 offset:2048
	ds_read_b128 v[220:223], v129 offset:3072
	global_load_lds_dwordx4 v[158:159], off
	v_lshl_add_u64 v[158:159], v[224:225], 0, s[46:47]
	s_add_i32 m0, s49, 0x2000
	s_nop 0
	global_load_lds_dwordx4 v[158:159], off
	s_barrier
	s_waitcnt lgkmcnt(0)
	s_waitcnt lgkmcnt(0)
	v_mfma_f32_16x16x32_bf16 v[116:119], v[208:211], v[176:179], v[116:119]
	v_mfma_f32_16x16x32_bf16 v[108:111], v[216:219], v[176:179], v[108:111]
	v_mfma_f32_16x16x32_bf16 v[100:103], v[208:211], v[184:187], v[100:103]
	v_mfma_f32_16x16x32_bf16 v[92:95], v[216:219], v[184:187], v[92:95]
	v_mfma_f32_16x16x32_bf16 v[84:87], v[208:211], v[192:195], v[84:87]
	v_mfma_f32_16x16x32_bf16 v[76:79], v[216:219], v[192:195], v[76:79]
	v_mfma_f32_16x16x32_bf16 v[68:71], v[208:211], v[200:203], v[68:71]
	v_mfma_f32_16x16x32_bf16 v[64:67], v[216:219], v[200:203], v[64:67]
	v_mfma_f32_16x16x32_bf16 v[116:119], v[212:215], v[180:183], v[116:119]
	v_mfma_f32_16x16x32_bf16 v[108:111], v[220:223], v[180:183], v[108:111]
	v_mfma_f32_16x16x32_bf16 v[100:103], v[212:215], v[188:191], v[100:103]
	v_mfma_f32_16x16x32_bf16 v[92:95], v[220:223], v[188:191], v[92:95]
	v_mfma_f32_16x16x32_bf16 v[84:87], v[212:215], v[196:199], v[84:87]
	v_mfma_f32_16x16x32_bf16 v[76:79], v[220:223], v[196:199], v[76:79]
	v_mfma_f32_16x16x32_bf16 v[68:71], v[212:215], v[204:207], v[68:71]
	v_mfma_f32_16x16x32_bf16 v[64:67], v[220:223], v[204:207], v[64:67]
	s_mov_b32 m0, s7
	v_lshl_add_u64 v[158:159], v[226:227], 0, s[46:47]
	s_barrier
	ds_read_b128 v[176:179], v165 offset:49152
	ds_read_b128 v[180:183], v165 offset:50176
	ds_read_b128 v[184:187], v165 offset:51200
	ds_read_b128 v[188:191], v165 offset:52224
	ds_read_b128 v[192:195], v165 offset:53248
	ds_read_b128 v[196:199], v165 offset:54272
	ds_read_b128 v[200:203], v165 offset:55296
	ds_read_b128 v[204:207], v165 offset:56320
	global_load_lds_dwordx4 v[158:159], off
	v_lshl_add_u64 v[158:159], v[228:229], 0, s[46:47]
	s_mov_b32 m0, s68
	s_nop 0
	global_load_lds_dwordx4 v[158:159], off
	s_barrier
; #define PG8_STAGE(bufoff, gbase, voff) do { _Pragma("unroll") for (int _i = 0; _i < 2; ++_i) \
;         __builtin_amdgcn_global_load_lds((const unsigned*)((const char*)(gbase) + (voff)[_i]), (LAS unsigned*)(lds + (bufoff) + ldsw + _i * 8192), 16, 0, 0); } while (0)
; #define PG8_LDA(dst, b, h) do { _Pragma("unroll") for (int m = 0; m < 4; ++m) _Pragma("unroll") for (int k = 0; k < 2; ++k) dst[m][k] = *(const LAS bf16x8*)(lds + PG8_SA(b, h) + aoff + m * 2048 + k * 1024); } while (0)
; #define PG8_MMA(ai, bj, At, Bt) do { __builtin_amdgcn_s_setprio(1); _Pragma("unroll") for (int m = 0; m < 4; ++m) _Pragma("unroll") for (int n = 0; n < 2; ++n) _Pragma("unroll") for (int k = 0; k < 2; ++k) \
;         acc[ai][bj][m][n] = __builtin_amdgcn_mfma_f32_16x16x32_bf16(Bt[n][k], At[m][k], acc[ai][bj][m][n], 0, 0, 0); __builtin_amdgcn_s_setprio(0); } while (0)
; #define PG8_WAIT_V(n) asm volatile("s_waitcnt vmcnt(" #n ")" ::: "memory")
; #define PG8_WAIT_L(n) asm volatile("s_waitcnt lgkmcnt(" #n ")" ::: "memory")
; #define PG8_BAR __builtin_amdgcn_s_barrier()
; #define PG8_SCHED __builtin_amdgcn_sched_barrier(0)
; template <class Epi, class Sched>
; __device__ __forceinline__ void gemm_phase(LAS unsigned char* lds, const Gemm g, const Sched& S, const Epi& E) {
;     ...
;             PG8_BAR; PG8_WAIT_L(0); PG8_MMA(0, 1, At, B1); PG8_BAR;
;             PG8_LDA(At, 1, 1); PG8_STAGE(PG8_SA(1, 0), a3, voffA);
;             PG8_BAR; PG8_WAIT_L(0); PG8_MMA(1, 0, At, B0); PG8_BAR; PG8_SCHED;
;             PG8_STAGE(PG8_SB(1, 1), b3 + hstepB, voffB);
;             PG8_WAIT_V(6); PG8_BAR; PG8_MMA(1, 1, At, B1); PG8_BAR;
;         }
;         if constexpr (!Epi::AFTER_DRAIN) E(acc, cur, wr, wc, fr, fq);
;     __device__ __forceinline__ void operator()(const f32x4 (&acc)[2][2][4][2], const Unit& u, int wr, int wc, int fr, int fq) const {
;         const int cl = wc * 32 + 8 * fq;
;         const int row0 = u.pm * BM + wr * 64 + fr, t = u.pn;
;         if (t < 4) run<0>(acc, Z + ZSLAB(2 * t, 0), 128, ZSLAB(1, 0), row0, cl);
;         else if (t < 8) run<1>(acc, Z + ZSLAB(2 * t, 0), 128, ZSLAB(1, 0), row0, cl);
;         else if (t < 16) {
	s_waitcnt lgkmcnt(0)
	s_waitcnt lgkmcnt(0)
	v_mfma_f32_16x16x32_bf16 v[60:63], v[150:153], v[176:179], v[60:63]
	v_mfma_f32_16x16x32_bf16 v[56:59], v[168:171], v[176:179], v[56:59]
	v_mfma_f32_16x16x32_bf16 v[48:51], v[150:153], v[184:187], v[48:51]
	v_mfma_f32_16x16x32_bf16 v[40:43], v[168:171], v[184:187], v[40:43]
	v_mfma_f32_16x16x32_bf16 v[36:39], v[150:153], v[192:195], v[36:39]
	v_mfma_f32_16x16x32_bf16 v[28:31], v[168:171], v[192:195], v[28:31]
	v_mfma_f32_16x16x32_bf16 v[20:23], v[150:153], v[200:203], v[20:23]
	v_mfma_f32_16x16x32_bf16 v[12:15], v[168:171], v[200:203], v[12:15]
	v_mfma_f32_16x16x32_bf16 v[60:63], v[154:157], v[180:183], v[60:63]
	v_mfma_f32_16x16x32_bf16 v[56:59], v[172:175], v[180:183], v[56:59]
	v_mfma_f32_16x16x32_bf16 v[48:51], v[154:157], v[188:191], v[48:51]
	v_mfma_f32_16x16x32_bf16 v[40:43], v[172:175], v[188:191], v[40:43]
	v_mfma_f32_16x16x32_bf16 v[36:39], v[154:157], v[196:199], v[36:39]
	v_mfma_f32_16x16x32_bf16 v[28:31], v[172:175], v[196:199], v[28:31]
	v_mfma_f32_16x16x32_bf16 v[20:23], v[154:157], v[204:207], v[20:23]
	v_mfma_f32_16x16x32_bf16 v[12:15], v[172:175], v[204:207], v[12:15]
	s_barrier
	s_add_u32 s72, s72, 0x40080
	s_addc_u32 s73, s73, 0
	s_add_i32 s49, s51, s95
	v_lshl_add_u64 v[150:151], s[72:73], 0, v[138:139]
	s_mov_b32 m0, s49
	s_nop 0
	global_load_lds_dwordx4 v[150:151], off
	v_lshl_add_u64 v[150:151], s[72:73], 0, v[134:135]
	s_add_i32 m0, s49, 0x2000
	s_nop 0
	global_load_lds_dwordx4 v[150:151], off
	s_waitcnt vmcnt(6)
	s_barrier
	v_mfma_f32_16x16x32_bf16 v[52:55], v[208:211], v[176:179], v[52:55]
	v_mfma_f32_16x16x32_bf16 v[44:47], v[216:219], v[176:179], v[44:47]
	v_mfma_f32_16x16x32_bf16 v[32:35], v[208:211], v[184:187], v[32:35]
	v_mfma_f32_16x16x32_bf16 v[24:27], v[216:219], v[184:187], v[24:27]
	v_mfma_f32_16x16x32_bf16 v[16:19], v[208:211], v[192:195], v[16:19]
	v_mfma_f32_16x16x32_bf16 v[8:11], v[216:219], v[192:195], v[8:11]
	v_mfma_f32_16x16x32_bf16 v[4:7], v[208:211], v[200:203], v[4:7]
	v_mfma_f32_16x16x32_bf16 v[0:3], v[216:219], v[200:203], v[0:3]
	v_mfma_f32_16x16x32_bf16 v[52:55], v[212:215], v[180:183], v[52:55]
	v_mfma_f32_16x16x32_bf16 v[44:47], v[220:223], v[180:183], v[44:47]
	v_mfma_f32_16x16x32_bf16 v[32:35], v[212:215], v[188:191], v[32:35]
	v_mfma_f32_16x16x32_bf16 v[24:27], v[220:223], v[188:191], v[24:27]
	v_mfma_f32_16x16x32_bf16 v[16:19], v[212:215], v[196:199], v[16:19]
	v_mfma_f32_16x16x32_bf16 v[8:11], v[220:223], v[196:199], v[8:11]
	v_mfma_f32_16x16x32_bf16 v[4:7], v[212:215], v[204:207], v[4:7]
	v_mfma_f32_16x16x32_bf16 v[0:3], v[220:223], v[204:207], v[0:3]
	s_add_i32 s29, s29, 2
	s_add_u32 s70, s70, 0x100
	s_addc_u32 s71, s71, 0
	s_add_u32 s27, s27, 0x100
	s_addc_u32 s28, s28, 0
	s_cmp_gt_u32 s29, 13
	s_barrier
	s_cbranch_scc0 .LBB0_140
	v_lshl_add_u32 v150, s2, 8, v163
	s_cmp_gt_i32 s87, 3
	s_mov_b64 s[70:71], -1
	s_cbranch_scc0 .LBB0_167
	s_cmp_gt_u32 s87, 7
	s_cbranch_scc0 .LBB0_164
	v_mul_f32_e32 v129, v124, v124
	v_mul_f32_e32 v149, v120, v120
	v_mul_f32_e32 v151, v125, v125
	v_mul_f32_e32 v152, v121, v121
	v_mul_f32_e32 v153, v126, v126
	v_mul_f32_e32 v154, v122, v122
	v_mul_f32_e32 v155, v127, v127
	v_mul_f32_e32 v156, v123, v123
	s_cmp_gt_u32 s87, 15
	v_fmamk_f32 v174, v129, 0xbdd2d3e7, v160
	v_fmamk_f32 v173, v149, 0xbdd2d3e7, v160
	v_fmamk_f32 v172, v151, 0xbdd2d3e7, v160
	v_fmamk_f32 v171, v152, 0xbdd2d3e7, v160
	v_fmamk_f32 v170, v153, 0xbdd2d3e7, v160
	v_fmamk_f32 v169, v154, 0xbdd2d3e7, v160
	v_fmamk_f32 v168, v155, 0xbdd2d3e7, v160
	v_fmamk_f32 v166, v156, 0xbdd2d3e7, v160
	s_cbranch_scc0 .LBB0_161
; __device__ __forceinline__ unsigned cvt_pk_bf16(float lo, float hi) { unsigned r; asm volatile("v_cvt_pk_bf16_f32 %0, %1, %2" : "=v"(r) : "v"(lo), "v"(hi)); return r; }
; __device__ __forceinline__ float act_silu(float v) { return v * fast_sigmoid(v); }
; __device__ __forceinline__ float act_gelu_tanh(float v) {
;     constexpr float c1 = -2.0f * LOG2E * 0.7978845608028654f, c2 = c1 * 0.044715f;
;     const float t = v * v, p = fmaf(t, c2, c1);
;     return v * __builtin_amdgcn_rcpf(1.0f + __builtin_amdgcn_exp2f(v * p));
; }
; #pragma unroll
;         for (int ai = 0; ai < 2; ++ai)
; #pragma unroll
;             for (int m = 0; m < 4; ++m) { bf16_t* rowp = base + (size_t)(row0 + ai * HALF + m * 16) * ldc + col0; float ps = 0.f, pq = 0.f;
; #pragma unroll
;                 for (int bj = 0; bj < 2; ++bj) { f32x4 v0 = acc[ai][bj][m][0], v1 = acc[ai][bj][m][1];
;                     if (ACT == 1) {
; #pragma unroll
;                         for (int j = 0; j < 4; ++j) { v0[j] = act_silu(v0[j]); v1[j] = act_silu(v1[j]); } }
;                     if (ACT == 2) {
; #pragma unroll
;                         for (int j = 0; j < 4; ++j) { v0[j] = act_gelu_tanh(v0[j]); v1[j] = act_gelu_tanh(v1[j]); } }
;                     if (STATS) {
; #pragma unroll
;                         for (int j = 0; j < 4; ++j) { ps += v0[j] + v1[j]; pq += v0[j] * v0[j] + v1[j] * v1[j]; } }
;                     u32x4 w; w.x = cvt_pk_bf16(v0[0], v0[1]); w.y = cvt_pk_bf16(v0[2], v0[3]); w.z = cvt_pk_bf16(v1[0], v1[1]); w.w = cvt_pk_bf16(v1[2], v1[3]);
;                     *(u32x4*)(rowp + bj * bjstep) = w; }
;                 if (STATS) {
;                     ps += __shfl_xor(ps, 16); ps += __shfl_xor(ps, 32); pq += __shfl_xor(pq, 16); pq += __shfl_xor(pq, 32);
;                     if (fq == 0) { f32x2 o; o[0] = ps; o[1] = pq; *(f32x2*)(st + ((size_t)(row0 + ai * HALF + m * 16) * 16 + slot) * 2) = o; } } }
	s_lshl_b32 s98, s24, 9
	v_add_u32_e32 v240, s98, v167
	v_lshlrev_b32_e32 v241, 5, v240
	v_lshlrev_b32_e32 v242, 4, v240
	s_add_u32 s98, s22, 0x3400000
	s_addc_u32 s99, s23, 0
	s_add_u32 s100, s22, 0x200000
	s_addc_u32 s101, s23, 0
	global_load_dwordx4 v[244:247], v241, s[98:99]
	global_load_dwordx4 v[248:251], v241, s[98:99] offset:16
	global_load_dwordx4 v[236:239], v242, s[100:101]
	v_mul_f32_e32 v129, v124, v174
	s_add_i32 s2, s87, -16
	v_exp_f32_e32 v129, v129
	v_mul_f32_e32 v149, v120, v173
	s_lshl_b32 s11, s2, 1
	v_exp_f32_e32 v149, v149
	s_add_i32 s14, s11, 24
	s_lshl_b64 s[26:27], s[14:15], 22
	v_ashrrev_i32_e32 v151, 31, v150
	v_lshl_add_u64 v[152:153], v[142:143], 0, s[26:27]
	v_lshlrev_b64 v[154:155], 8, v[150:151]
	v_add_f32_e32 v129, 1.0, v129
	v_lshl_add_u64 v[158:159], v[152:153], 0, v[154:155]
	v_rcp_f32_e32 v154, v129
	v_add_f32_e32 v129, 1.0, v149
	v_rcp_f32_e32 v155, v129
	v_mov_b32_e32 v156, v124
	v_mov_b32_e32 v157, v120
	v_mul_f32_e32 v181, v116, v116
	v_pk_mul_f32 v[176:177], v[156:157], v[154:155]
	v_fmamk_f32 v181, v181, 0xbdd2d3e7, v160
	v_mul_f32_e32 v182, v108, v108
	v_mul_f32_e32 v181, v116, v181
	v_fmamk_f32 v182, v182, 0xbdd2d3e7, v160
	v_pk_fma_f32 v[154:155], v[156:157], v[154:155], v[176:177] op_sel:[0,0,1] op_sel_hi:[1,1,0]
	v_mul_f32_e32 v156, v117, v117
	v_exp_f32_e32 v181, v181
	v_mul_f32_e32 v182, v108, v182
	v_fmamk_f32 v156, v156, 0xbdd2d3e7, v160
	v_mul_f32_e32 v157, v109, v109
	v_exp_f32_e32 v182, v182
	v_mul_f32_e32 v156, v117, v156
	v_fmamk_f32 v157, v157, 0xbdd2d3e7, v160
	v_mul_f32_e32 v129, v125, v172
	v_exp_f32_e32 v156, v156
	v_mul_f32_e32 v157, v109, v157
	v_exp_f32_e32 v129, v129
	v_mul_f32_e32 v149, v121, v171
	v_exp_f32_e32 v157, v157
	v_exp_f32_e32 v149, v149
	v_add_f32_e32 v155, 1.0, v181
	v_rcp_f32_e32 v194, v155
	v_add_f32_e32 v155, 1.0, v182
	v_rcp_f32_e32 v195, v155
	v_add_f32_e32 v155, 1.0, v156
	v_mul_f32_e32 v156, v118, v118
	v_add_f32_e32 v129, 1.0, v129
	v_rcp_f32_e32 v196, v155
	v_add_f32_e32 v155, 1.0, v157
	v_fmamk_f32 v156, v156, 0xbdd2d3e7, v160
	v_mul_f32_e32 v157, v110, v110
	v_rcp_f32_e32 v178, v129
	v_add_f32_e32 v129, 1.0, v149
	v_mul_f32_e32 v149, v126, v170
	v_mul_f32_e32 v175, v122, v169
	v_mul_f32_e32 v156, v118, v156
	v_fmamk_f32 v157, v157, 0xbdd2d3e7, v160
	v_exp_f32_e32 v149, v149
	v_exp_f32_e32 v175, v175
	v_mul_f32_e32 v179, v123, v166
	v_exp_f32_e32 v156, v156
	v_mul_f32_e32 v157, v110, v157
	v_exp_f32_e32 v179, v179
	v_exp_f32_e32 v157, v157
	v_rcp_f32_e32 v180, v129
	v_add_f32_e32 v129, 1.0, v149
	v_add_f32_e32 v149, 1.0, v175
	v_mul_f32_e32 v175, v127, v168
	v_rcp_f32_e32 v197, v155
	v_add_f32_e32 v155, 1.0, v156
	v_mul_f32_e32 v156, v119, v119
	v_exp_f32_e32 v175, v175
	v_add_f32_e32 v179, 1.0, v179
	v_rcp_f32_e32 v198, v155
	v_add_f32_e32 v155, 1.0, v157
	v_fmamk_f32 v156, v156, 0xbdd2d3e7, v160
	v_mul_f32_e32 v157, v111, v111
	v_rcp_f32_e32 v179, v179
	v_mul_f32_e32 v156, v119, v156
	v_fmamk_f32 v157, v157, 0xbdd2d3e7, v160
	v_exp_f32_e32 v156, v156
	v_mul_f32_e32 v157, v111, v157
	v_exp_f32_e32 v157, v157
	v_rcp_f32_e32 v129, v129
	v_rcp_f32_e32 v149, v149
	v_add_f32_e32 v175, 1.0, v175
	v_rcp_f32_e32 v175, v175
	v_mul_f32_e32 v186, v123, v179
	v_mov_b32_e32 v188, v125
	v_mov_b32_e32 v189, v176
	v_mov_b32_e32 v179, v176
	v_mov_b32_e32 v192, v121
	v_mov_b32_e32 v193, v177
	v_mov_b32_e32 v181, v177
	v_rcp_f32_e32 v199, v155
	v_add_f32_e32 v155, 1.0, v156
	v_pk_mul_f32 v[190:191], v[188:189], v[178:179]
	v_pk_mul_f32 v[180:181], v[192:193], v[180:181]
	v_rcp_f32_e32 v200, v155
	v_add_f32_e32 v155, 1.0, v157
	v_pk_fma_f32 v[178:179], v[188:189], v[178:179], v[180:181]
	v_pk_mul_f32 v[188:189], v[190:191], v[190:191]
	v_pk_mul_f32 v[192:193], v[180:181], v[180:181]
	v_rcp_f32_e32 v201, v155
	v_mul_f32_e32 v156, v126, v129
	v_mul_f32_e32 v182, v122, v149
	v_mov_b32_e32 v155, v188
	v_mov_b32_e32 v129, v192
	v_mul_f32_e32 v184, v127, v175
	v_pk_add_f32 v[154:155], v[154:155], v[128:129]
	v_mul_f32_e32 v157, v156, v156
	v_mul_f32_e32 v183, v182, v182
	v_pk_add_f32 v[154:155], v[178:179], v[154:155]
	v_pk_add_f32 v[178:179], v[156:157], v[182:183]
	v_mul_f32_e32 v185, v184, v184
	v_mul_f32_e32 v187, v186, v186
	v_pk_add_f32 v[154:155], v[178:179], v[154:155]
	v_pk_add_f32 v[178:179], v[184:185], v[186:187]
	v_and_b32_e32 v149, 64, v162
	v_pk_add_f32 v[178:179], v[178:179], v[154:155]
	v_cvt_pk_bf16_f32 v154, v176, v190
	v_cvt_pk_bf16_f32 v155, v156, v184
	v_cvt_pk_bf16_f32 v156, v177, v180
	v_cvt_pk_bf16_f32 v157, v182, v186
	global_store_dwordx4 v[158:159], v[154:157], off
	v_mul_f32_e32 v176, v117, v196
	v_mul_f32_e32 v180, v109, v197
	v_mul_f32_e32 v154, v116, v194
	v_mul_f32_e32 v156, v108, v195
	v_mul_f32_e32 v155, v154, v154
	v_mul_f32_e32 v157, v156, v156
	v_mul_f32_e32 v182, v118, v198
	v_mul_f32_e32 v184, v110, v199
	v_pk_add_f32 v[190:191], v[154:155], v[156:157]
	v_mul_f32_e32 v177, v176, v176
	v_mul_f32_e32 v181, v180, v180
	v_mul_f32_e32 v186, v119, v200
	v_mul_f32_e32 v188, v111, v201
	v_pk_add_f32 v[178:179], v[178:179], v[190:191]
	v_pk_add_f32 v[190:191], v[176:177], v[180:181]
	v_mul_f32_e32 v183, v182, v182
	v_mul_f32_e32 v185, v184, v184
	v_xor_b32_e32 v129, 16, v162
	v_add_u32_e32 v157, 64, v149
	v_pk_add_f32 v[178:179], v[190:191], v[178:179]
	v_pk_add_f32 v[190:191], v[182:183], v[184:185]
	v_mul_f32_e32 v187, v186, v186
	v_mul_f32_e32 v189, v188, v188
	v_cmp_lt_i32_e32 vcc, v129, v157
	v_pk_add_f32 v[178:179], v[190:191], v[178:179]
	v_pk_add_f32 v[190:191], v[186:187], v[188:189]
	v_cndmask_b32_e32 v129, v162, v129, vcc
	v_pk_add_f32 v[190:191], v[190:191], v[178:179]
	v_lshlrev_b32_e32 v149, 2, v129
	ds_bpermute_b32 v192, v149, v190
	ds_bpermute_b32 v193, v149, v191
	v_xor_b32_e32 v129, 32, v162
	v_cmp_lt_i32_e32 vcc, v129, v157
	v_cvt_pk_bf16_f32 v176, v154, v176
	s_lshl_b32 s2, s2, 3
	s_waitcnt lgkmcnt(0)
	v_pk_add_f32 v[154:155], v[190:191], v[192:193]
	v_cndmask_b32_e32 v129, v162, v129, vcc
	v_lshlrev_b32_e32 v175, 2, v129
	v_cvt_pk_bf16_f32 v177, v182, v186
	v_cvt_pk_bf16_f32 v178, v156, v180
	ds_bpermute_b32 v156, v175, v154
	ds_bpermute_b32 v157, v175, v155
	s_or_b32 s14, s2, s3
	s_lshl_b64 s[26:27], s[14:15], 2
	s_add_u32 s70, s80, s26
	v_add_co_u32_e32 v158, vcc, s88, v158
	s_addc_u32 s71, s81, s27
	s_nop 0
	v_addc_co_u32_e32 v159, vcc, 0, v159, vcc
	v_cvt_pk_bf16_f32 v179, v184, v188
	global_store_dwordx4 v[158:159], v[176:179], off
	s_and_saveexec_b64 s[72:73], s[0:1]
	s_cbranch_execz .LBB0_146
	s_waitcnt lgkmcnt(0)
	v_pk_add_f32 v[154:155], v[154:155], v[156:157]
	v_lshlrev_b64 v[156:157], 7, v[150:151]
	v_lshl_add_u64 v[156:157], s[70:71], 0, v[156:157]
	global_store_dwordx2 v[156:157], v[154:155], off

; #define PG8_WAIT_V(n) asm volatile("s_waitcnt vmcnt(" #n ")" ::: "memory")
; #define PG8_BAR __builtin_amdgcn_s_barrier()
; template <class Epi, class Sched>
; __device__ __forceinline__ void gemm_phase(LAS unsigned char* lds, const Gemm g, const Sched& S, const Epi& E) {
;     ...
;     PG8_WAIT_V(0);
;     if (wr == 0) PG8_BAR;
;     PG8_BAR;
.LBB0_169:
	s_setprio 0
	s_waitcnt vmcnt(0)
	s_cmpk_gt_u32 s94, 0xff
	s_cbranch_scc1 .LBB0_130
	s_barrier
	s_branch .LBB0_130
